# grid barrier: non-leader blocks poll the top-level generation word directly (one release hop less); first-barrier count loads issued together; on top of NSA bias-read hoist
# speedup vs baseline: 1.0052x; 1.0043x over previous
; __device__ __forceinline__ unsigned xb_ld(unsigned* p)              { return __hip_atomic_load(p, __ATOMIC_RELAXED, __HIP_MEMORY_SCOPE_AGENT); }
; __device__ __forceinline__ void xcd_barrier_complete(unsigned* bar, unsigned x, unsigned& nloc, unsigned& nx) {
;     const unsigned G = gridDim.x * gridDim.y * gridDim.z;
;     unsigned sum, cnt, mine, sp = 0u;
;     for (;;) {
;         sum = 0u; cnt = 0u; mine = 0u;
; #pragma unroll
;         for (unsigned j = 0; j < 16; ++j) { const unsigned c = xb_ld(&bar[XB_XCNT(j)]); sum += c; cnt += (c > 0u) ? 1u : 0u; mine = (j == x) ? c : mine; }
;         if (sum == G) break;
;         __builtin_amdgcn_s_sleep(1);
;         if ((++sp & 255u) == 0u) { if (xb_ld(&bar[XB_TMO])) break; if (sp > XB_SPIN_CAP) { atomicAdd(&bar[XB_TMO], 1u); break; } }
;     }
.LBB0_1049:
	v_readlane_b32 s16, v253, 28
	v_readlane_b32 s17, v253, 29
	s_mov_b64 s[30:31], -1
	s_mov_b64 s[34:35], -1
	s_waitcnt lgkmcnt(0)
	s_nop 1
	global_load_dword v0, v177, s[16:17] sc1
	v_readlane_b32 s16, v253, 30
	v_readlane_b32 s17, v253, 31
	s_nop 4
	global_load_dword v1, v177, s[16:17] sc1
	v_readlane_b32 s16, v253, 32
	v_readlane_b32 s17, v253, 33
	s_nop 4
	global_load_dword v2, v177, s[16:17] sc1
	v_readlane_b32 s16, v253, 34
	v_readlane_b32 s17, v253, 35
	s_nop 4
	global_load_dword v3, v177, s[16:17] sc1
	v_readlane_b32 s16, v253, 36
	v_readlane_b32 s17, v253, 37
	s_nop 4
	global_load_dword v4, v177, s[16:17] sc1
	v_readlane_b32 s16, v253, 38
	v_readlane_b32 s17, v253, 39
	s_nop 4
	global_load_dword v5, v177, s[16:17] sc1
	v_readlane_b32 s16, v253, 40
	v_readlane_b32 s17, v253, 41
	s_nop 4
	global_load_dword v6, v177, s[16:17] sc1
	v_readlane_b32 s16, v253, 42
	v_readlane_b32 s17, v253, 43
	s_nop 4
	global_load_dword v7, v177, s[16:17] sc1
	v_readlane_b32 s16, v253, 44
	v_readlane_b32 s17, v253, 45
	s_nop 4
	global_load_dword v8, v177, s[16:17] sc1
	v_readlane_b32 s16, v253, 46
	v_readlane_b32 s17, v253, 47
	s_nop 4
	global_load_dword v9, v177, s[16:17] sc1
	v_readlane_b32 s16, v253, 48
	v_readlane_b32 s17, v253, 49
	s_nop 4
	global_load_dword v10, v177, s[16:17] sc1
	v_readlane_b32 s16, v253, 50
	v_readlane_b32 s17, v253, 51
	s_nop 4
	global_load_dword v11, v177, s[16:17] sc1
	v_readlane_b32 s16, v253, 52
	v_readlane_b32 s17, v253, 53
	s_nop 4
	global_load_dword v12, v177, s[16:17] sc1
	v_readlane_b32 s16, v253, 54
	v_readlane_b32 s17, v253, 55
	s_nop 4
	global_load_dword v13, v177, s[16:17] sc1
	v_readlane_b32 s16, v253, 56
	v_readlane_b32 s17, v253, 57
	s_nop 4
	global_load_dword v14, v177, s[16:17] sc1
	v_readlane_b32 s16, v253, 58
	v_readlane_b32 s17, v253, 59
	s_nop 4
	global_load_dword v15, v177, s[16:17] sc1
	v_readlane_b32 s16, v253, 25
	s_waitcnt vmcnt(0)
	v_add_u32_e32 v16, v1, v0
	v_add_u32_e32 v16, v16, v2
	v_add_u32_e32 v16, v16, v3
	v_add_u32_e32 v16, v16, v4
	v_add_u32_e32 v16, v16, v5
	v_add_u32_e32 v16, v16, v6
	v_add_u32_e32 v16, v16, v7
	v_add_u32_e32 v16, v16, v8
	v_add_u32_e32 v16, v16, v9
	v_add_u32_e32 v16, v16, v10
	v_add_u32_e32 v16, v16, v11
	v_add_u32_e32 v16, v16, v12
	v_add_u32_e32 v16, v16, v13
	v_add_u32_e32 v16, v16, v14
	v_add_u32_e32 v16, v16, v15
	v_cmp_eq_u32_e32 vcc, s16, v16
	s_cbranch_vccnz .LBB0_1048
	s_and_b32 s16, s36, 0xff
	s_cmp_eq_u32 s16, 0
	s_mov_b64 s[16:17], -1
	s_sleep 1
	s_cbranch_scc0 .LBB0_1053
	v_readlane_b32 s16, v253, 26
	v_readlane_b32 s17, v253, 27
	s_nop 4
	global_load_dword v16, v177, s[16:17] sc1
	s_waitcnt vmcnt(0)
	v_cmp_eq_u32_e32 vcc, 0, v16
	s_cbranch_vccnz .LBB0_1055
	s_mov_b64 s[16:17], 0

; __device__ __forceinline__ unsigned xb_ld(unsigned* p)              { return __hip_atomic_load(p, __ATOMIC_RELAXED, __HIP_MEMORY_SCOPE_AGENT); }
; __device__ __forceinline__ unsigned xb_add(unsigned* p, unsigned v) { return __hip_atomic_fetch_add(p, v, __ATOMIC_RELAXED, __HIP_MEMORY_SCOPE_AGENT); }
; #define XB_SPIN(cond, bar) do { unsigned _sp = 0; while (cond) { __builtin_amdgcn_s_sleep(1); \
;     if ((++_sp & 255u) == 0u) { if (xb_ld(&(bar)[XB_TMO])) break; if (_sp > XB_SPIN_CAP) { atomicAdd(&(bar)[XB_TMO], 1u); break; } } } } while (0)
; __device__ __forceinline__ void xcd_barrier(const XcdBarrier& b) {
;     ...
;         unsigned nloc = b.st[0], nx = b.st[1];
;         if (nloc == 0u) { xcd_barrier_complete(bar, b.x, nloc, nx); b.st[0] = nloc; b.st[1] = nx; }
;         const unsigned old = xb_add(&bar[XB_XSUB(b.x)], 1u);
;         const unsigned gen = old / nloc;
;         if (old + 1u == (gen + 1u) * nloc) {
;             __builtin_amdgcn_fence(__ATOMIC_RELEASE, "agent");
;             asm volatile("s_waitcnt vmcnt(0)" ::: "memory");
;             const unsigned og = xb_add(&bar[XB_TOP], 1u);
;             const unsigned tg = og / nx;
;             if (og + 1u == (tg + 1u) * nx) xb_add(&bar[XB_TOPGEN], 1u);
;             else XB_SPIN(xb_ld(&bar[XB_TOPGEN]) == tg, bar);
;             __builtin_amdgcn_fence(__ATOMIC_ACQUIRE, "agent");
;             xb_add(&bar[XB_XGEN(b.x)], 1u);
;             asm volatile("s_waitcnt vmcnt(0)" ::: "memory");
;         } else {
;             XB_SPIN(xb_ld(&bar[XB_XGEN(b.x)]) == gen, bar);
.LBB0_1088:
	s_or_b64 exec, exec, s[16:17]
	v_cvt_f32_u32_e32 v4, v2
	s_waitcnt vmcnt(0)
	v_readfirstlane_b32 s16, v3
	v_sub_u32_e32 v3, 0, v2
	v_rcp_iflag_f32_e32 v4, v4
	v_add_u32_e32 v5, s16, v1
	v_mul_f32_e32 v4, 0x4f7ffffe, v4
	v_cvt_u32_f32_e32 v4, v4
	v_mul_lo_u32 v1, v3, v4
	v_mul_hi_u32 v1, v4, v1
	v_add_u32_e32 v1, v4, v1
	v_mul_hi_u32 v1, v5, v1
	v_mul_lo_u32 v3, v1, v2
	v_sub_u32_e32 v3, v5, v3
	v_add_u32_e32 v4, 1, v1
	v_cmp_ge_u32_e32 vcc, v3, v2
	s_nop 1
	v_cndmask_b32_e32 v1, v1, v4, vcc
	v_sub_u32_e32 v4, v3, v2
	v_cndmask_b32_e32 v3, v3, v4, vcc
	v_add_u32_e32 v4, 1, v1
	v_cmp_ge_u32_e32 vcc, v3, v2
	v_add_u32_e32 v3, 1, v5
	s_nop 0
	v_cndmask_b32_e32 v1, v1, v4, vcc
	v_mul_lo_u32 v4, v2, v1
	v_add_u32_e32 v2, v4, v2
	v_cmp_ne_u32_e32 vcc, v3, v2
	s_and_saveexec_b64 s[16:17], vcc
	s_xor_b64 s[30:31], exec, s[16:17]
	s_cbranch_execz .LBB0_1102
	v_readlane_b32 s16, v254, 34
	v_readlane_b32 s17, v254, 35
	s_waitcnt lgkmcnt(0)
	s_nop 3
	global_load_dword v0, v177, s[16:17] sc1
	s_waitcnt vmcnt(0)
	v_cmp_eq_u32_e32 vcc, v0, v1
	s_and_saveexec_b64 s[34:35], vcc
	s_cbranch_execz .LBB0_1101
	s_mov_b32 s46, 1
	s_mov_b64 s[36:37], 0
	s_branch .LBB0_1092

; __device__ __forceinline__ unsigned xb_ld(unsigned* p)              { return __hip_atomic_load(p, __ATOMIC_RELAXED, __HIP_MEMORY_SCOPE_AGENT); }
; #define XB_SPIN(cond, bar) do { unsigned _sp = 0; while (cond) { __builtin_amdgcn_s_sleep(1); \
;     if ((++_sp & 255u) == 0u) { if (xb_ld(&(bar)[XB_TMO])) break; if (_sp > XB_SPIN_CAP) { atomicAdd(&(bar)[XB_TMO], 1u); break; } } } } while (0)
; __device__ __forceinline__ void xcd_barrier(const XcdBarrier& b) {
;     ...
;             XB_SPIN(xb_ld(&bar[XB_XGEN(b.x)]) == gen, bar);
.LBB0_1096:
	v_readlane_b32 s16, v254, 34
	v_readlane_b32 s17, v254, 35
	s_add_i32 s46, s46, 1
	s_mov_b64 s[94:95], -1
	s_nop 2
	global_load_dword v0, v177, s[16:17] sc1
	s_waitcnt vmcnt(0)
	v_cmp_ne_u32_e32 vcc, v0, v1
	s_orn2_b64 s[42:43], vcc, exec
	s_branch .LBB0_1091
